# grid barriers P5->P6 and P6->P7 replaced by placement-independent blockIdx%8 group barriers (token-tile-local dependencies), on top of GEMM loop edits
# baseline (speedup 1.0000x reference)
; #define LAS __attribute__((address_space(3)))
; __global__ void __launch_bounds__(512, 2) mk_fwd(Args args) {
;     extern __shared__ __attribute__((aligned(16))) unsigned char lds_raw[];
;     cg::grid_group grid = cg::this_grid();
;     LAS unsigned char* lds = (LAS unsigned char*)lds_raw;
;     volatile LAS unsigned long long* ptab = (volatile LAS unsigned long long*)(lds + 143360);
;     if (threadIdx.x == 0) { ((volatile LAS unsigned*)(lds + LDS_BARST))[0] = 0u; ((volatile LAS unsigned*)(lds + LDS_BARST))[1] = 0u;
;         ptab[0] = (unsigned long long)args.in[0]; ptab[1] = (unsigned long long)args.in[1]; ptab[2] = (unsigned long long)args.in[2]; ptab[3] = (unsigned long long)args.in[3];
;         ptab[4] = (unsigned long long)args.in[4]; ptab[5] = (unsigned long long)args.in[5]; ptab[6] = (unsigned long long)args.in[6]; ptab[7] = (unsigned long long)args.in[7];
;         ptab[8] = (unsigned long long)args.in[8]; ptab[9] = (unsigned long long)args.in[9]; ptab[10] = (unsigned long long)args.in[10]; ptab[11] = (unsigned long long)args.in[11];
;         ptab[12] = (unsigned long long)args.in[12]; ptab[13] = (unsigned long long)args.in[13]; ptab[14] = (unsigned long long)args.in[14]; ptab[15] = (unsigned long long)args.in[15];
;         ptab[16] = (unsigned long long)args.out; ptab[17] = (unsigned long long)args.ws;
;     }
_Z6mk_fwd4Args:
	s_load_dwordx4 s[24:27], s[0:1], 0x88
	s_load_dword s21, s[0:1], 0x98
	s_add_u32 s4, s0, 0x90
	s_mov_b32 s92, 0
	v_and_b32_e32 v230, 0x3ff, v0
	s_mov_b32 s20, s2
	s_addc_u32 s5, s1, 0
	v_cmp_eq_u32_e64 s[18:19], 0, v230
	s_and_saveexec_b64 s[2:3], s[18:19]
	s_cbranch_execz .LBB0_2
	s_load_dwordx16 s[52:67], s[0:1], 0x0
	s_load_dwordx16 s[36:51], s[0:1], 0x40
	s_load_dwordx2 s[6:7], s[0:1], 0x80
	s_add_i32 s0, 0, 0x23100
	v_mov_b32_e32 v1, 0
	v_mov_b32_e32 v34, s0
	s_add_i32 s0, 0, 0x23104
	ds_write_b32 v34, v1
	v_mov_b32_e32 v34, s0
	s_add_i32 s0, 0, 0x23000
	s_waitcnt lgkmcnt(0)
	v_mov_b32_e32 v18, s52
	v_mov_b32_e32 v19, s53
	ds_write_b32 v34, v1
	v_mov_b32_e32 v1, s0
	s_add_i32 s0, 0, 0x23008
	v_mov_b32_e32 v20, s54
	v_mov_b32_e32 v21, s55
	ds_write_b64 v1, v[18:19]
	v_mov_b32_e32 v1, s0
	s_add_i32 s0, 0, 0x23010
	v_mov_b32_e32 v22, s56
	v_mov_b32_e32 v23, s57
	ds_write_b64 v1, v[20:21]
	v_mov_b32_e32 v1, s0
	s_add_i32 s0, 0, 0x23018
	v_mov_b32_e32 v24, s58
	v_mov_b32_e32 v25, s59
	ds_write_b64 v1, v[22:23]
	v_mov_b32_e32 v1, s0
	s_add_i32 s0, 0, 0x23020
	v_mov_b32_e32 v26, s60
	v_mov_b32_e32 v27, s61
	ds_write_b64 v1, v[24:25]
	v_mov_b32_e32 v1, s0
	s_add_i32 s0, 0, 0x23028
	v_mov_b32_e32 v28, s62
	v_mov_b32_e32 v29, s63
	ds_write_b64 v1, v[26:27]
	v_mov_b32_e32 v1, s0
	s_add_i32 s0, 0, 0x23030
	v_mov_b32_e32 v30, s64
	v_mov_b32_e32 v31, s65
	ds_write_b64 v1, v[28:29]
	v_mov_b32_e32 v1, s0
	s_add_i32 s0, 0, 0x23038
	v_mov_b32_e32 v32, s66
	v_mov_b32_e32 v33, s67
	ds_write_b64 v1, v[30:31]
	v_mov_b32_e32 v1, s0
	s_add_i32 s0, 0, 0x23040
	v_mov_b32_e32 v2, s36
	v_mov_b32_e32 v3, s37
	ds_write_b64 v1, v[32:33]
	v_mov_b32_e32 v1, s0
	s_add_i32 s0, 0, 0x23048
	v_mov_b32_e32 v4, s38
	v_mov_b32_e32 v5, s39
	ds_write_b64 v1, v[2:3]
	v_mov_b32_e32 v1, s0
	s_add_i32 s0, 0, 0x23050
	v_mov_b32_e32 v6, s40
	v_mov_b32_e32 v7, s41
	ds_write_b64 v1, v[4:5]
	v_mov_b32_e32 v1, s0
	s_add_i32 s0, 0, 0x23058
	v_mov_b32_e32 v8, s42
	v_mov_b32_e32 v9, s43
	ds_write_b64 v1, v[6:7]
	v_mov_b32_e32 v1, s0
	s_add_i32 s0, 0, 0x23060
	v_mov_b32_e32 v10, s44
	v_mov_b32_e32 v11, s45
	ds_write_b64 v1, v[8:9]
	v_mov_b32_e32 v1, s0
	s_add_i32 s0, 0, 0x23068
	v_mov_b32_e32 v12, s46
	v_mov_b32_e32 v13, s47
	ds_write_b64 v1, v[10:11]
	v_mov_b32_e32 v1, s0
	s_add_i32 s0, 0, 0x23070
	v_mov_b32_e32 v14, s48
	v_mov_b32_e32 v15, s49
	ds_write_b64 v1, v[12:13]
	v_mov_b32_e32 v1, s0
	s_add_i32 s0, 0, 0x23078
	v_mov_b32_e32 v16, s50
	v_mov_b32_e32 v17, s51
	ds_write_b64 v1, v[14:15]
	v_mov_b32_e32 v1, s0
	s_add_i32 s0, 0, 0x23080
	ds_write_b64 v1, v[16:17]
	v_mov_b32_e32 v1, s0
	v_mov_b64_e32 v[2:3], s[6:7]
	s_add_i32 s0, 0, 0x23088
	ds_write_b64 v1, v[2:3]
	v_mov_b32_e32 v1, s0
	v_mov_b64_e32 v[2:3], s[24:25]
	ds_write_b64 v1, v[2:3]

; #define PG8_WAIT_V(n) asm volatile("s_waitcnt vmcnt(" #n ")" ::: "memory")
; template <class Epi, class Sched, bool ALIGN_EPI = false, bool SP2 = false>
; __device__ __forceinline__ void gemm_phase(PG8_LAS unsigned char* lds, const Gemm g, const Sched& S, const Epi& E) {
;     int tid_ = threadIdx.x; asm volatile("" : "+v"(tid_)); const int tid = tid_, wid = __builtin_amdgcn_readfirstlane(tid >> 6), lane = tid & 63, wr = wid >> 2, wc = wid & 3, fr = lane & 15, fq = lane >> 4;
;     const int K = g.K, nt = K / BK;
;     unsigned voffA[2], voffB[2];
; #pragma unroll
;     for (int i = 0; i < 2; ++i) { int R, C; stage_rc(tid * 16 + i * 8192, R, C); const int Rb = Epi::PERM ? ((R & ~31) + perm32(R & 31)) : R;
;         voffA[i] = (unsigned)(R * K + C) * 2u; voffB[i] = (unsigned)(Rb * K + C) * 2u; }
;     const size_t kstep = (size_t)(BK * 2);
;     const size_t hstep = (size_t)HALF * K * 2;
;     const size_t tstep = 2 * hstep;
;     const unsigned ldsw = (unsigned)wid * 1024u;
;     const int aoff = lds_byte(wr * 64 + fr, fq * 8), boff = lds_byte(wc * 32 + fr, fq * 8);
;     ...
;     Unit cur, nxt; int ui = 0;
;     if (!S.next(0, cur)) return;
;     f32x4 acc[2][2][4][2];
; #pragma unroll
;     for (int a = 0; a < 2; ++a)
; #pragma unroll
;         for (int b = 0; b < 2; ++b)
; #pragma unroll
;             for (int m = 0; m < 4; ++m)
; #pragma unroll
;                 for (int n = 0; n < 2; ++n) acc[a][b][m][n] = (f32x4){0.f, 0.f, 0.f, 0.f};
;     bf16x8 At[4][2], B0[2][2], B1[2][2];
;     const char* cA = (const char*)g.A + (size_t)cur.pm * tstep; const char* cB = (const char*)g.Bt + (size_t)cur.pn * tstep;
;     S.a_ready(cur);
;     if constexpr (SP2) {
;         PG8_STAGE(PG8_SB(0, 0), cB, voffB); PG8_STAGE(PG8_SB(0, 1), cB + hstep, voffB); PG8_STAGE(PG8_SA(0, 0), cA, voffA); PG8_STAGE(PG8_SA(0, 1), cA + hstep, voffA);
;         if (wr == 1) PG8_BAR;
;         PG8_WAIT_V(2); PG8_BAR;
; __global__ void __launch_bounds__(512, 2) mk_fwd(Args args) {
;     ...
;         GSYNC();
; _Pragma("unroll 1") for (int rep_ = 0; rep_ < REP_P6; ++rep_)
;         { PH_IDS unsigned char* ws = WS_;
;           pg8::Gemm g{(const bf16*)(ws + WS_XB), (const bf16*)(ws + WS_WFI) + (size_t)l * FF2 * DMOD, T, FF2, DMOD}; pg8::StaticOrder S; S.init(T, FF2, G, bid);
;           pg8::EpiSwiglu E{(bf16*)(ws + WS_P), FFH, (const unsigned long long*)(ws + WS_SS) + (size_t)(2 * l + 1) * T};
.LBB0_644:
	s_waitcnt vmcnt(0) lgkmcnt(0)
	s_barrier
	s_and_saveexec_b64 s[84:85], s[18:19]
	s_cbranch_execz .Lgb_done_0
	buffer_wbl2 sc1
	s_waitcnt vmcnt(0)
	v_mov_b32_e32 v0, 0x23088
	ds_read_b64 v[0:1], v0
	s_waitcnt lgkmcnt(0)
	v_readfirstlane_b32 s86, v0
	v_readfirstlane_b32 s87, v1
	s_and_b32 s88, s20, 7
	s_lshl_b32 s89, s88, 8
	s_add_u32 s86, s86, s89
	s_addc_u32 s87, s87, 0
	s_add_u32 s86, s86, 0x35090000
	s_addc_u32 s87, s87, 0
	s_sub_u32 s88, s26, s88
	s_add_u32 s88, s88, 7
	s_lshr_b32 s88, s88, 3
	s_add_u32 s92, s92, 1
	s_mul_i32 s89, s92, s88
	v_mov_b32_e32 v0, 0
	v_mov_b32_e32 v1, 1
	global_atomic_add v0, v1, s[86:87]
	s_mov_b32 s91, 0
.Lgb_spin_0:
	global_load_dword v2, v0, s[86:87] sc1
	s_waitcnt vmcnt(0)
	s_nop 0
	v_readfirstlane_b32 s90, v2
	s_cmp_ge_u32 s90, s89
	s_cbranch_scc1 .Lgb_rel_0
	s_sleep 1
	s_add_u32 s91, s91, 1
	s_cmp_lt_u32 s91, 0x40000
	s_cbranch_scc1 .Lgb_spin_0
.Lgb_rel_0:
	buffer_inv sc1
	s_waitcnt vmcnt(0)
.Lgb_done_0:
	s_or_b64 exec, exec, s[84:85]
	s_barrier
	s_add_i32 s36, 0, 0x23088
	s_mov_b32 s33, s20
	s_mov_b32 s37, s26
	v_mov_b32_e32 v0, s36
	ds_read_b64 v[0:1], v0
	v_mov_b32_e32 v9, v230
	s_cmpk_lt_i32 s33, 0xb00
	v_readfirstlane_b32 s3, v9
	s_waitcnt lgkmcnt(0)
	v_readfirstlane_b32 s7, v1
	v_readfirstlane_b32 s6, v0
	s_cbranch_scc0 .LBB0_712
	v_lshlrev_b32_e32 v0, 4, v9
	v_add_u32_e32 v1, 0x2000, v0
	v_ashrrev_i32_e32 v2, 31, v1
	v_lshrrev_b32_e32 v2, 22, v2
	v_add_u32_e32 v2, v1, v2
	v_ashrrev_i32_e32 v8, 10, v2
	v_mul_i32_i24_e32 v2, 0x400, v8
	v_sub_u32_e32 v1, v1, v2
	v_lshrrev_b32_e32 v2, 4, v1
	v_bitop3_b32 v1, v2, v1, 32 bitop3:0x6c
	v_ashrrev_i32_e32 v2, 31, v1
	v_lshrrev_b32_e32 v2, 26, v2
	v_add_u32_e32 v2, v1, v2
	v_lshlrev_b32_e32 v3, 3, v8
	v_ashrrev_i32_e32 v10, 6, v2
	v_and_b32_e32 v3, -16, v3
	v_add_u32_e32 v3, v10, v3
	v_and_b32_e32 v4, 3, v10
	s_mov_b32 s0, 0xfffe0
	v_lshrrev_b32_e32 v5, 2, v3
	v_lshlrev_b32_e32 v6, 1, v3
	v_and_b32_e32 v2, 0xc0, v2
	v_and_or_b32 v4, v3, s0, v4
	v_and_b32_e32 v5, 4, v5
	v_and_b32_e32 v6, 24, v6
	v_sub_u32_e32 v1, v1, v2
	v_mov_b32_e32 v2, 1
	v_or3_b32 v4, v4, v5, v6
	v_lshlrev_b32_e32 v5, 5, v8
	v_ashrrev_i16_sdwa v1, v2, sext(v1) dst_sel:DWORD dst_unused:UNUSED_PAD src0_sel:DWORD src1_sel:BYTE_0
	v_and_b32_e32 v5, 32, v5
	v_bfe_i32 v11, v1, 0, 16
	v_add_lshl_u32 v1, v5, v11, 1
	v_lshl_add_u32 v128, v4, 12, v1
	v_lshl_add_u32 v130, v3, 12, v1
	v_bfe_i32 v1, v9, 27, 1
	v_lshrrev_b32_e32 v1, 22, v1
	v_add_u32_e32 v1, v0, v1
	v_and_b32_e32 v1, 0xfffffc00, v1
	v_sub_u32_e32 v0, v0, v1
	v_lshrrev_b32_e32 v1, 4, v0
	v_ashrrev_i32_e32 v3, 31, v9
	v_bitop3_b32 v0, v1, v0, 32 bitop3:0x6c
	v_lshrrev_b32_e32 v3, 26, v3
	v_ashrrev_i32_e32 v1, 31, v0
	v_add_u32_e32 v3, v9, v3
	s_add_u32 s38, s6, 0x18600000
	v_lshrrev_b32_e32 v1, 26, v1
	v_ashrrev_i32_e32 v13, 6, v3
	s_addc_u32 s39, s7, 0
	v_add_u32_e32 v1, v0, v1
	v_lshlrev_b32_e32 v3, 3, v13
	s_add_u32 s40, s6, 0x7e00000
	v_ashrrev_i32_e32 v12, 6, v1
	v_and_b32_e32 v3, -16, v3
	s_addc_u32 s41, s7, 0
	v_add_u32_e32 v3, v12, v3
	v_and_b32_e32 v4, 3, v12
	s_ashr_i32 s43, s33, 31
	v_and_or_b32 v4, v3, s0, v4
	s_lshr_b32 s0, s43, 29
	s_add_i32 s0, s33, s0
	s_ashr_i32 s8, s3, 6
	s_ashr_i32 s1, s0, 3
	s_and_b32 s0, s0, -8
	s_ashr_i32 s10, s3, 8
	s_lshl_b32 s42, s8, 10
	s_sub_i32 s0, s33, s0
	s_cmp_lt_i32 s0, 0
	s_movk_i32 s44, 0x161
	s_cselect_b32 s2, s44, 0x160
	s_mul_i32 s0, s0, s2
	s_add_i32 s0, s0, s1
	s_mul_hi_i32 s1, s0, 0x2e8ba2e9
	s_lshr_b32 s2, s1, 31
	s_ashr_i32 s1, s1, 6
	s_add_i32 s1, s1, s2
	s_lshl_b32 s4, s1, 3
	s_mulk_i32 s1, 0x160
	s_sub_i32 s0, s0, s1
	s_bfe_u32 s1, s0, 0x3001c
	s_add_i32 s1, s0, s1
	s_sext_i32_i16 s2, s1
	s_and_b32 s1, s1, 0xfff8
	s_sub_i32 s0, s0, s1
	s_sext_i32_i16 s0, s0
	v_lshrrev_b32_e32 v5, 2, v3
	v_lshlrev_b32_e32 v6, 1, v3
	v_and_b32_e32 v1, 0xc0, v1
	s_lshr_b32 s2, s2, 3
	s_add_i32 s24, s4, s0
	v_and_b32_e32 v5, 4, v5
	v_and_b32_e32 v6, 24, v6
	v_sub_u32_e32 v0, v0, v1
	s_ashr_i32 s25, s24, 31
	s_bfe_i64 s[4:5], s[2:3], 0x100000
	v_or3_b32 v4, v4, v5, v6
	v_lshlrev_b32_e32 v5, 5, v13
	v_ashrrev_i16_sdwa v0, v2, sext(v0) dst_sel:DWORD dst_unused:UNUSED_PAD src0_sel:DWORD src1_sel:BYTE_0
	s_lshl_b64 s[0:1], s[24:25], 20
	s_lshl_b64 s[4:5], s[4:5], 20
	v_and_b32_e32 v5, 32, v5
	v_bfe_i32 v14, v0, 0, 16
	s_add_u32 s30, s40, s4
	v_add_lshl_u32 v0, v5, v14, 1
	s_addc_u32 s31, s41, s5
	s_add_i32 s25, s42, 0
	v_lshl_add_u32 v132, v4, 12, v0
	s_add_i32 m0, s25, 0x10000
	v_lshl_add_u32 v134, v3, 12, v0
	global_load_lds_dwordx4 v132, s[30:31]
	s_add_i32 m0, s25, 0x12000
	s_add_u32 s4, s30, 0x80000
	global_load_lds_dwordx4 v128, s[30:31]
	s_addc_u32 s5, s31, 0
	s_add_i32 m0, s25, 0x14000
	v_mov_b32_e32 v133, 0
	global_load_lds_dwordx4 v132, s[4:5]
	s_add_i32 m0, s25, 0x16000
	s_add_u32 s28, s38, s0
	s_addc_u32 s29, s39, s1
	s_add_i32 s45, s25, 0x2000
	global_load_lds_dwordx4 v128, s[4:5]
	s_mov_b32 m0, s25
	s_add_u32 s0, s28, 0x80000
	global_load_lds_dwordx4 v134, s[28:29]
	s_mov_b32 m0, s45
	s_addc_u32 s1, s29, 0
	s_add_i32 s46, s25, 0x4000
	global_load_lds_dwordx4 v130, s[28:29]
	s_mov_b32 m0, s46
	s_add_i32 s47, s25, 0x6000
	global_load_lds_dwordx4 v134, s[0:1]
	s_mov_b32 m0, s47
	v_mov_b32_e32 v129, v133
	global_load_lds_dwordx4 v130, s[0:1]
	v_mov_b32_e32 v135, v133
	v_mov_b32_e32 v131, v133
	s_cmp_eq_u32 s10, 1
	v_lshl_add_u64 v[6:7], s[30:31], 0, v[132:133]
	v_lshl_add_u64 v[4:5], s[30:31], 0, v[128:129]
	v_lshl_add_u64 v[0:1], s[28:29], 0, v[134:135]
	s_cselect_b64 s[0:1], -1, 0
	s_cmp_lg_u32 s10, 1
	v_lshl_add_u64 v[2:3], s[28:29], 0, v[130:131]
	s_cbranch_scc1 .LBB0_699
	s_barrier

;     __host__ __device__ bool next(int i, Unit& u) const {
;         const long L = (long)i * G + c; if (L >= nwg) return false;
;         int wgid = (int)L; { const int q = nwg / NXCD, r = nwg % NXCD, xcd = wgid % NXCD, off = wgid / NXCD; wgid = (xcd < r ? xcd * (q + 1) : r * (q + 1) + (xcd - r) * q) + off; }
;         const int nig = WGM * nN, gid = wgid / nig, fm = gid * WGM, gsz = (nM - fm) < WGM ? (nM - fm) : WGM;
;         u.pm = fm + ((wgid % nig) % gsz); u.pn = (wgid % nig) / gsz; return true;
; __global__ void __launch_bounds__(512, 2) mk_fwd(Args args) {
;     ...
;         GSYNC();
;         { PH_IDS unsigned char* ws = WS_;
;           pg8::Gemm g{(const bf16*)(ws + WS_P), (const bf16*)(ws + WS_WFO) + (size_t)l * DMOD * FFH, T, DMOD, FFH}; pg8::StaticOrder S; S.init(T, DMOD, G, bid);
.Lgb_done_1:
	s_or_b64 exec, exec, s[84:85]
	s_barrier
	s_add_i32 s0, 0, 0x23088
	s_mov_b32 s33, s20
	s_mov_b32 s34, s26
	v_mov_b32_e32 v0, s0
	ds_read_b64 v[0:1], v0
	v_mov_b32_e32 v8, v230
	s_cmpk_lt_i32 s33, 0x200
	s_cselect_b64 s[0:1], -1, 0
	s_waitcnt lgkmcnt(0)
	v_readfirstlane_b32 s5, v1
	v_readfirstlane_b32 s6, v0
	s_cmpk_gt_i32 s33, 0x1ff
	v_readfirstlane_b32 s4, v8
	s_cbranch_scc1 .LBB0_771
	s_ashr_i32 s2, s33, 31
	s_lshr_b32 s2, s2, 29
	s_add_i32 s9, s33, s2
	s_and_b32 s2, s9, -8
	s_sub_i32 s7, s33, s2
	s_cmp_gt_i32 s7, -1
	s_cbranch_scc0 .LBB0_768
	s_lshl_b32 s8, s7, 6
	s_ashr_i32 s2, s9, 3
	s_cbranch_execz .LBB0_769
	s_branch .LBB0_770

; #define PG8_STAGE(bufoff, gbase, voff) do { _Pragma("unroll") for (int _i = 0; _i < 2; ++_i) \
;         __builtin_amdgcn_global_load_lds((const unsigned*)((const char*)(gbase) + (voff)[_i]), (PG8_LAS unsigned*)(lds + (bufoff) + ldsw + _i * 8192), 16, 0, 0); } while (0)
; #define PG8_WAIT_V(n) asm volatile("s_waitcnt vmcnt(" #n ")" ::: "memory")
; template <class Epi, class Sched, bool ALIGN_EPI = false, bool SP2 = false>
; __device__ __forceinline__ void gemm_phase(PG8_LAS unsigned char* lds, const Gemm g, const Sched& S, const Epi& E) {
;     int tid_ = threadIdx.x; asm volatile("" : "+v"(tid_)); const int tid = tid_, wid = __builtin_amdgcn_readfirstlane(tid >> 6), lane = tid & 63, wr = wid >> 2, wc = wid & 3, fr = lane & 15, fq = lane >> 4;
;     const int K = g.K, nt = K / BK;
;     unsigned voffA[2], voffB[2];
; #pragma unroll
;     for (int i = 0; i < 2; ++i) { int R, C; stage_rc(tid * 16 + i * 8192, R, C); const int Rb = Epi::PERM ? ((R & ~31) + perm32(R & 31)) : R;
;         voffA[i] = (unsigned)(R * K + C) * 2u; voffB[i] = (unsigned)(Rb * K + C) * 2u; }
;     const size_t kstep = (size_t)(BK * 2);
;     const size_t hstep = (size_t)HALF * K * 2;
;     const size_t tstep = 2 * hstep;
;     const unsigned ldsw = (unsigned)wid * 1024u;
;     const int aoff = lds_byte(wr * 64 + fr, fq * 8), boff = lds_byte(wc * 32 + fr, fq * 8);
;     ...
;     Unit cur, nxt; int ui = 0;
;     if (!S.next(0, cur)) return;
;     f32x4 acc[2][2][4][2];
; #pragma unroll
;     for (int a = 0; a < 2; ++a)
; #pragma unroll
;         for (int b = 0; b < 2; ++b)
; #pragma unroll
;             for (int m = 0; m < 4; ++m)
; #pragma unroll
;                 for (int n = 0; n < 2; ++n) acc[a][b][m][n] = (f32x4){0.f, 0.f, 0.f, 0.f};
;     bf16x8 At[4][2], B0[2][2], B1[2][2];
;     const char* cA = (const char*)g.A + (size_t)cur.pm * tstep; const char* cB = (const char*)g.Bt + (size_t)cur.pn * tstep;
;     S.a_ready(cur);
;     if constexpr (SP2) {
;         PG8_STAGE(PG8_SB(0, 0), cB, voffB); PG8_STAGE(PG8_SB(0, 1), cB + hstep, voffB); PG8_STAGE(PG8_SA(0, 0), cA, voffA); PG8_STAGE(PG8_SA(0, 1), cA + hstep, voffA);
;         if (wr == 1) PG8_BAR;
;         PG8_WAIT_V(2); PG8_BAR;
;         PG8_STAGE(PG8_SB(1, 0), cB + kstep, voffB); PG8_STAGE(PG8_SA(1, 0), cA + kstep, voffA); PG8_STAGE(PG8_SB(1, 1), cB + hstep + kstep, voffB);
;         PG8_WAIT_V(6); PG8_BAR;
.Lgb_done_2:
	s_or_b64 exec, exec, s[84:85]
	s_barrier
	s_add_i32 s36, 0, 0x23088
	s_mov_b32 s33, s20
	s_mov_b32 s37, s26
	v_mov_b32_e32 v0, s36
	ds_read_b64 v[0:1], v0
	v_mov_b32_e32 v9, v230
	s_cmpk_lt_i32 s33, 0xb00
	v_readfirstlane_b32 s3, v9
	s_waitcnt lgkmcnt(0)
	v_readfirstlane_b32 s7, v1
	v_readfirstlane_b32 s6, v0
	s_cbranch_scc0 .LBB0_1434
	v_lshlrev_b32_e32 v0, 4, v9
	v_add_u32_e32 v1, 0x2000, v0
	v_ashrrev_i32_e32 v2, 31, v1
	v_lshrrev_b32_e32 v2, 22, v2
	v_add_u32_e32 v2, v1, v2
	v_ashrrev_i32_e32 v8, 10, v2
	v_mul_i32_i24_e32 v2, 0x400, v8
	v_sub_u32_e32 v1, v1, v2
	v_lshrrev_b32_e32 v2, 4, v1
	v_bitop3_b32 v1, v2, v1, 32 bitop3:0x6c
	v_ashrrev_i32_e32 v2, 31, v1
	v_lshrrev_b32_e32 v2, 26, v2
	v_add_u32_e32 v2, v1, v2
	v_lshlrev_b32_e32 v3, 3, v8
	v_ashrrev_i32_e32 v10, 6, v2
	v_and_b32_e32 v3, -16, v3
	v_add_u32_e32 v3, v10, v3
	v_and_b32_e32 v4, 3, v10
	s_mov_b32 s0, 0xfffe0
	v_lshrrev_b32_e32 v5, 2, v3
	v_lshlrev_b32_e32 v6, 1, v3
	v_and_b32_e32 v2, 0xc0, v2
	v_and_or_b32 v4, v3, s0, v4
	v_and_b32_e32 v5, 4, v5
	v_and_b32_e32 v6, 24, v6
	v_sub_u32_e32 v1, v1, v2
	v_mov_b32_e32 v2, 1
	v_or3_b32 v4, v4, v5, v6
	v_lshlrev_b32_e32 v5, 5, v8
	v_ashrrev_i16_sdwa v1, v2, sext(v1) dst_sel:DWORD dst_unused:UNUSED_PAD src0_sel:DWORD src1_sel:BYTE_0
	v_and_b32_e32 v5, 32, v5
	v_bfe_i32 v11, v1, 0, 16
	v_add_lshl_u32 v1, v5, v11, 1
	v_lshl_add_u32 v128, v4, 12, v1
	v_lshl_add_u32 v130, v3, 12, v1
	v_bfe_i32 v1, v9, 27, 1
	v_lshrrev_b32_e32 v1, 22, v1
	v_add_u32_e32 v1, v0, v1
	v_and_b32_e32 v1, 0xfffffc00, v1
	v_sub_u32_e32 v0, v0, v1
	v_lshrrev_b32_e32 v1, 4, v0
	v_ashrrev_i32_e32 v3, 31, v9
	v_bitop3_b32 v0, v1, v0, 32 bitop3:0x6c
	v_lshrrev_b32_e32 v3, 26, v3
	v_ashrrev_i32_e32 v1, 31, v0
	v_add_u32_e32 v3, v9, v3
	s_add_u32 s38, s6, 0x18600000
	v_lshrrev_b32_e32 v1, 26, v1
	v_ashrrev_i32_e32 v13, 6, v3
	s_addc_u32 s39, s7, 0
	v_add_u32_e32 v1, v0, v1
	v_lshlrev_b32_e32 v3, 3, v13
	s_add_u32 s40, s6, 0xaa00000
	v_ashrrev_i32_e32 v12, 6, v1
	v_and_b32_e32 v3, -16, v3
	s_addc_u32 s41, s7, 0
	v_add_u32_e32 v3, v12, v3
	v_and_b32_e32 v4, 3, v12
	s_ashr_i32 s43, s33, 31
	v_and_or_b32 v4, v3, s0, v4
	s_lshr_b32 s0, s43, 29
	s_add_i32 s0, s33, s0
	s_ashr_i32 s8, s3, 6
	s_ashr_i32 s1, s0, 3
	s_and_b32 s0, s0, -8
	s_ashr_i32 s10, s3, 8
	s_lshl_b32 s42, s8, 10
	s_sub_i32 s0, s33, s0
	s_cmp_lt_i32 s0, 0
	s_movk_i32 s44, 0x161
	s_cselect_b32 s2, s44, 0x160
	s_mul_i32 s0, s0, s2
	s_add_i32 s0, s0, s1
	s_mul_hi_i32 s1, s0, 0x2e8ba2e9
	s_lshr_b32 s2, s1, 31
	s_ashr_i32 s1, s1, 6
	s_add_i32 s1, s1, s2
	s_lshl_b32 s4, s1, 3
	s_mulk_i32 s1, 0x160
	s_sub_i32 s0, s0, s1
	s_bfe_u32 s1, s0, 0x3001c
	s_add_i32 s1, s0, s1
	s_sext_i32_i16 s2, s1
	s_and_b32 s1, s1, 0xfff8
	s_sub_i32 s0, s0, s1
	s_sext_i32_i16 s0, s0
	v_lshrrev_b32_e32 v5, 2, v3
	v_lshlrev_b32_e32 v6, 1, v3
	v_and_b32_e32 v1, 0xc0, v1
	s_lshr_b32 s2, s2, 3
	s_add_i32 s24, s4, s0
	v_and_b32_e32 v5, 4, v5
	v_and_b32_e32 v6, 24, v6
	v_sub_u32_e32 v0, v0, v1
	s_ashr_i32 s25, s24, 31
	s_bfe_i64 s[4:5], s[2:3], 0x100000
	v_or3_b32 v4, v4, v5, v6
	v_lshlrev_b32_e32 v5, 5, v13
	v_ashrrev_i16_sdwa v0, v2, sext(v0) dst_sel:DWORD dst_unused:UNUSED_PAD src0_sel:DWORD src1_sel:BYTE_0
	s_lshl_b64 s[0:1], s[24:25], 20
	s_lshl_b64 s[4:5], s[4:5], 20
	v_and_b32_e32 v5, 32, v5
	v_bfe_i32 v14, v0, 0, 16
	s_add_u32 s30, s40, s4
	v_add_lshl_u32 v0, v5, v14, 1
	s_addc_u32 s31, s41, s5
	s_add_i32 s25, s42, 0
	v_lshl_add_u32 v132, v4, 12, v0
	s_add_i32 m0, s25, 0x10000
	v_lshl_add_u32 v134, v3, 12, v0
	global_load_lds_dwordx4 v132, s[30:31]
	s_add_i32 m0, s25, 0x12000
	s_add_u32 s4, s30, 0x80000
	global_load_lds_dwordx4 v128, s[30:31]
	s_addc_u32 s5, s31, 0
	s_add_i32 m0, s25, 0x14000
	v_mov_b32_e32 v133, 0
	global_load_lds_dwordx4 v132, s[4:5]
	s_add_i32 m0, s25, 0x16000
	s_add_u32 s28, s38, s0
	s_addc_u32 s29, s39, s1
	s_add_i32 s45, s25, 0x2000
	global_load_lds_dwordx4 v128, s[4:5]
	s_mov_b32 m0, s25
	s_add_u32 s0, s28, 0x80000
	global_load_lds_dwordx4 v134, s[28:29]
	s_mov_b32 m0, s45
	s_addc_u32 s1, s29, 0
	s_add_i32 s46, s25, 0x4000
	global_load_lds_dwordx4 v130, s[28:29]
	s_mov_b32 m0, s46
	s_add_i32 s47, s25, 0x6000
	global_load_lds_dwordx4 v134, s[0:1]
	s_mov_b32 m0, s47
	v_mov_b32_e32 v129, v133
	global_load_lds_dwordx4 v130, s[0:1]
	v_mov_b32_e32 v135, v133
	v_mov_b32_e32 v131, v133
	s_cmp_eq_u32 s10, 1
	v_lshl_add_u64 v[6:7], s[30:31], 0, v[132:133]
	v_lshl_add_u64 v[4:5], s[30:31], 0, v[128:129]
	v_lshl_add_u64 v[0:1], s[28:29], 0, v[134:135]
	s_cselect_b64 s[0:1], -1, 0
	s_cmp_lg_u32 s10, 1
	v_lshl_add_u64 v[2:3], s[28:29], 0, v[130:131]
	s_cbranch_scc1 .LBB0_1421
	s_barrier

; #define PG8_STAGE(bufoff, gbase, voff) do { _Pragma("unroll") for (int _i = 0; _i < 2; ++_i) \
;         __builtin_amdgcn_global_load_lds((const unsigned*)((const char*)(gbase) + (voff)[_i]), (PG8_LAS unsigned*)(lds + (bufoff) + ldsw + _i * 8192), 16, 0, 0); } while (0)
; #define PG8_WAIT_V(n) asm volatile("s_waitcnt vmcnt(" #n ")" ::: "memory")
; template <class Epi, class Sched, bool ALIGN_EPI = false, bool SP2 = false>
; __device__ __forceinline__ void gemm_phase(PG8_LAS unsigned char* lds, const Gemm g, const Sched& S, const Epi& E) {
;     int tid_ = threadIdx.x; asm volatile("" : "+v"(tid_)); const int tid = tid_, wid = __builtin_amdgcn_readfirstlane(tid >> 6), lane = tid & 63, wr = wid >> 2, wc = wid & 3, fr = lane & 15, fq = lane >> 4;
;     const int K = g.K, nt = K / BK;
;     unsigned voffA[2], voffB[2];
; #pragma unroll
;     for (int i = 0; i < 2; ++i) { int R, C; stage_rc(tid * 16 + i * 8192, R, C); const int Rb = Epi::PERM ? ((R & ~31) + perm32(R & 31)) : R;
;         voffA[i] = (unsigned)(R * K + C) * 2u; voffB[i] = (unsigned)(Rb * K + C) * 2u; }
;     const size_t kstep = (size_t)(BK * 2);
;     const size_t hstep = (size_t)HALF * K * 2;
;     const size_t tstep = 2 * hstep;
;     const unsigned ldsw = (unsigned)wid * 1024u;
;     const int aoff = lds_byte(wr * 64 + fr, fq * 8), boff = lds_byte(wc * 32 + fr, fq * 8);
;     ...
;     Unit cur, nxt; int ui = 0;
;     if (!S.next(0, cur)) return;
;     f32x4 acc[2][2][4][2];
; #pragma unroll
;     for (int a = 0; a < 2; ++a)
; #pragma unroll
;         for (int b = 0; b < 2; ++b)
; #pragma unroll
;             for (int m = 0; m < 4; ++m)
; #pragma unroll
;                 for (int n = 0; n < 2; ++n) acc[a][b][m][n] = (f32x4){0.f, 0.f, 0.f, 0.f};
;     bf16x8 At[4][2], B0[2][2], B1[2][2];
;     const char* cA = (const char*)g.A + (size_t)cur.pm * tstep; const char* cB = (const char*)g.Bt + (size_t)cur.pn * tstep;
;     S.a_ready(cur);
;     if constexpr (SP2) {
;         PG8_STAGE(PG8_SB(0, 0), cB, voffB); PG8_STAGE(PG8_SB(0, 1), cB + hstep, voffB); PG8_STAGE(PG8_SA(0, 0), cA, voffA); PG8_STAGE(PG8_SA(0, 1), cA + hstep, voffA);
;         if (wr == 1) PG8_BAR;
;         PG8_WAIT_V(2); PG8_BAR;
;         PG8_STAGE(PG8_SB(1, 0), cB + kstep, voffB); PG8_STAGE(PG8_SA(1, 0), cA + kstep, voffA); PG8_STAGE(PG8_SB(1, 1), cB + hstep + kstep, voffB);
;         PG8_WAIT_V(6); PG8_BAR;
.Lgb_done_4:
	s_or_b64 exec, exec, s[84:85]
	s_barrier
	s_add_i32 s36, 0, 0x23088
	s_mov_b32 s33, s20
	s_mov_b32 s37, s26
	v_mov_b32_e32 v0, s36
	ds_read_b64 v[0:1], v0
	v_mov_b32_e32 v9, v230
	s_cmpk_lt_i32 s33, 0xb00
	v_readfirstlane_b32 s3, v9
	s_waitcnt lgkmcnt(0)
	v_readfirstlane_b32 s7, v1
	v_readfirstlane_b32 s6, v0
	s_cbranch_scc0 .LBB0_2156
	v_lshlrev_b32_e32 v0, 4, v9
	v_add_u32_e32 v1, 0x2000, v0
	v_ashrrev_i32_e32 v2, 31, v1
	v_lshrrev_b32_e32 v2, 22, v2
	v_add_u32_e32 v2, v1, v2
	v_ashrrev_i32_e32 v8, 10, v2
	v_mul_i32_i24_e32 v2, 0x400, v8
	v_sub_u32_e32 v1, v1, v2
	v_lshrrev_b32_e32 v2, 4, v1
	v_bitop3_b32 v1, v2, v1, 32 bitop3:0x6c
	v_ashrrev_i32_e32 v2, 31, v1
	v_lshrrev_b32_e32 v2, 26, v2
	v_add_u32_e32 v2, v1, v2
	v_lshlrev_b32_e32 v3, 3, v8
	v_ashrrev_i32_e32 v10, 6, v2
	v_and_b32_e32 v3, -16, v3
	v_add_u32_e32 v3, v10, v3
	v_and_b32_e32 v4, 3, v10
	s_mov_b32 s0, 0xfffe0
	v_lshrrev_b32_e32 v5, 2, v3
	v_lshlrev_b32_e32 v6, 1, v3
	v_and_b32_e32 v2, 0xc0, v2
	v_and_or_b32 v4, v3, s0, v4
	v_and_b32_e32 v5, 4, v5
	v_and_b32_e32 v6, 24, v6
	v_sub_u32_e32 v1, v1, v2
	v_mov_b32_e32 v2, 1
	v_or3_b32 v4, v4, v5, v6
	v_lshlrev_b32_e32 v5, 5, v8
	v_ashrrev_i16_sdwa v1, v2, sext(v1) dst_sel:DWORD dst_unused:UNUSED_PAD src0_sel:DWORD src1_sel:BYTE_0
	v_and_b32_e32 v5, 32, v5
	v_bfe_i32 v11, v1, 0, 16
	v_add_lshl_u32 v1, v5, v11, 1
	v_lshl_add_u32 v128, v4, 12, v1
	v_lshl_add_u32 v130, v3, 12, v1
	v_bfe_i32 v1, v9, 27, 1
	v_lshrrev_b32_e32 v1, 22, v1
	v_add_u32_e32 v1, v0, v1
	v_and_b32_e32 v1, 0xfffffc00, v1
	v_sub_u32_e32 v0, v0, v1
	v_lshrrev_b32_e32 v1, 4, v0
	v_ashrrev_i32_e32 v3, 31, v9
	v_bitop3_b32 v0, v1, v0, 32 bitop3:0x6c
	v_lshrrev_b32_e32 v3, 26, v3
	v_ashrrev_i32_e32 v1, 31, v0
	v_add_u32_e32 v3, v9, v3
	s_add_u32 s38, s6, 0x18600000
	v_lshrrev_b32_e32 v1, 26, v1
	v_ashrrev_i32_e32 v13, 6, v3
	s_addc_u32 s39, s7, 0
	v_add_u32_e32 v1, v0, v1
	v_lshlrev_b32_e32 v3, 3, v13
	s_add_u32 s40, s6, 0xd600000
	v_ashrrev_i32_e32 v12, 6, v1
	v_and_b32_e32 v3, -16, v3
	s_addc_u32 s41, s7, 0
	v_add_u32_e32 v3, v12, v3
	v_and_b32_e32 v4, 3, v12
	s_ashr_i32 s43, s33, 31
	v_and_or_b32 v4, v3, s0, v4
	s_lshr_b32 s0, s43, 29
	s_add_i32 s0, s33, s0
	s_ashr_i32 s8, s3, 6
	s_ashr_i32 s1, s0, 3
	s_and_b32 s0, s0, -8
	s_ashr_i32 s10, s3, 8
	s_lshl_b32 s42, s8, 10
	s_sub_i32 s0, s33, s0
	s_cmp_lt_i32 s0, 0
	s_movk_i32 s44, 0x161
	s_cselect_b32 s2, s44, 0x160
	s_mul_i32 s0, s0, s2
	s_add_i32 s0, s0, s1
	s_mul_hi_i32 s1, s0, 0x2e8ba2e9
	s_lshr_b32 s2, s1, 31
	s_ashr_i32 s1, s1, 6
	s_add_i32 s1, s1, s2
	s_lshl_b32 s4, s1, 3
	s_mulk_i32 s1, 0x160
	s_sub_i32 s0, s0, s1
	s_bfe_u32 s1, s0, 0x3001c
	s_add_i32 s1, s0, s1
	s_sext_i32_i16 s2, s1
	s_and_b32 s1, s1, 0xfff8
	s_sub_i32 s0, s0, s1
	s_sext_i32_i16 s0, s0
	v_lshrrev_b32_e32 v5, 2, v3
	v_lshlrev_b32_e32 v6, 1, v3
	v_and_b32_e32 v1, 0xc0, v1
	s_lshr_b32 s2, s2, 3
	s_add_i32 s24, s4, s0
	v_and_b32_e32 v5, 4, v5
	v_and_b32_e32 v6, 24, v6
	v_sub_u32_e32 v0, v0, v1
	s_ashr_i32 s25, s24, 31
	s_bfe_i64 s[4:5], s[2:3], 0x100000
	v_or3_b32 v4, v4, v5, v6
	v_lshlrev_b32_e32 v5, 5, v13
	v_ashrrev_i16_sdwa v0, v2, sext(v0) dst_sel:DWORD dst_unused:UNUSED_PAD src0_sel:DWORD src1_sel:BYTE_0
	s_lshl_b64 s[0:1], s[24:25], 20
	s_lshl_b64 s[4:5], s[4:5], 20
	v_and_b32_e32 v5, 32, v5
	v_bfe_i32 v14, v0, 0, 16
	s_add_u32 s30, s40, s4
	v_add_lshl_u32 v0, v5, v14, 1
	s_addc_u32 s31, s41, s5
	s_add_i32 s25, s42, 0
	v_lshl_add_u32 v132, v4, 12, v0
	s_add_i32 m0, s25, 0x10000
	v_lshl_add_u32 v134, v3, 12, v0
	global_load_lds_dwordx4 v132, s[30:31]
	s_add_i32 m0, s25, 0x12000
	s_add_u32 s4, s30, 0x80000
	global_load_lds_dwordx4 v128, s[30:31]
	s_addc_u32 s5, s31, 0
	s_add_i32 m0, s25, 0x14000
	v_mov_b32_e32 v133, 0
	global_load_lds_dwordx4 v132, s[4:5]
	s_add_i32 m0, s25, 0x16000
	s_add_u32 s28, s38, s0
	s_addc_u32 s29, s39, s1
	s_add_i32 s45, s25, 0x2000
	global_load_lds_dwordx4 v128, s[4:5]
	s_mov_b32 m0, s25
	s_add_u32 s0, s28, 0x80000
	global_load_lds_dwordx4 v134, s[28:29]
	s_mov_b32 m0, s45
	s_addc_u32 s1, s29, 0
	s_add_i32 s46, s25, 0x4000
	global_load_lds_dwordx4 v130, s[28:29]
	s_mov_b32 m0, s46
	s_add_i32 s47, s25, 0x6000
	global_load_lds_dwordx4 v134, s[0:1]
	s_mov_b32 m0, s47
	v_mov_b32_e32 v129, v133
	global_load_lds_dwordx4 v130, s[0:1]
	v_mov_b32_e32 v135, v133
	v_mov_b32_e32 v131, v133
	s_cmp_eq_u32 s10, 1
	v_lshl_add_u64 v[6:7], s[30:31], 0, v[132:133]
	v_lshl_add_u64 v[4:5], s[30:31], 0, v[128:129]
	v_lshl_add_u64 v[0:1], s[28:29], 0, v[134:135]
	s_cselect_b64 s[0:1], -1, 0
	s_cmp_lg_u32 s10, 1
	v_lshl_add_u64 v[2:3], s[28:29], 0, v[130:131]
	s_cbranch_scc1 .LBB0_2143
	s_barrier

; #define PG8_STAGE(bufoff, gbase, voff) do { _Pragma("unroll") for (int _i = 0; _i < 2; ++_i) \
;         __builtin_amdgcn_global_load_lds((const unsigned*)((const char*)(gbase) + (voff)[_i]), (PG8_LAS unsigned*)(lds + (bufoff) + ldsw + _i * 8192), 16, 0, 0); } while (0)
; #define PG8_WAIT_V(n) asm volatile("s_waitcnt vmcnt(" #n ")" ::: "memory")
; template <class Epi, class Sched, bool ALIGN_EPI = false, bool SP2 = false>
; __device__ __forceinline__ void gemm_phase(PG8_LAS unsigned char* lds, const Gemm g, const Sched& S, const Epi& E) {
;     int tid_ = threadIdx.x; asm volatile("" : "+v"(tid_)); const int tid = tid_, wid = __builtin_amdgcn_readfirstlane(tid >> 6), lane = tid & 63, wr = wid >> 2, wc = wid & 3, fr = lane & 15, fq = lane >> 4;
;     const int K = g.K, nt = K / BK;
;     unsigned voffA[2], voffB[2];
; #pragma unroll
;     for (int i = 0; i < 2; ++i) { int R, C; stage_rc(tid * 16 + i * 8192, R, C); const int Rb = Epi::PERM ? ((R & ~31) + perm32(R & 31)) : R;
;         voffA[i] = (unsigned)(R * K + C) * 2u; voffB[i] = (unsigned)(Rb * K + C) * 2u; }
;     const size_t kstep = (size_t)(BK * 2);
;     const size_t hstep = (size_t)HALF * K * 2;
;     const size_t tstep = 2 * hstep;
;     const unsigned ldsw = (unsigned)wid * 1024u;
;     const int aoff = lds_byte(wr * 64 + fr, fq * 8), boff = lds_byte(wc * 32 + fr, fq * 8);
;     ...
;     Unit cur, nxt; int ui = 0;
;     if (!S.next(0, cur)) return;
;     f32x4 acc[2][2][4][2];
; #pragma unroll
;     for (int a = 0; a < 2; ++a)
; #pragma unroll
;         for (int b = 0; b < 2; ++b)
; #pragma unroll
;             for (int m = 0; m < 4; ++m)
; #pragma unroll
;                 for (int n = 0; n < 2; ++n) acc[a][b][m][n] = (f32x4){0.f, 0.f, 0.f, 0.f};
;     bf16x8 At[4][2], B0[2][2], B1[2][2];
;     const char* cA = (const char*)g.A + (size_t)cur.pm * tstep; const char* cB = (const char*)g.Bt + (size_t)cur.pn * tstep;
;     S.a_ready(cur);
;     if constexpr (SP2) {
;         PG8_STAGE(PG8_SB(0, 0), cB, voffB); PG8_STAGE(PG8_SB(0, 1), cB + hstep, voffB); PG8_STAGE(PG8_SA(0, 0), cA, voffA); PG8_STAGE(PG8_SA(0, 1), cA + hstep, voffA);
;         if (wr == 1) PG8_BAR;
;         PG8_WAIT_V(2); PG8_BAR;
;         PG8_STAGE(PG8_SB(1, 0), cB + kstep, voffB); PG8_STAGE(PG8_SA(1, 0), cA + kstep, voffA); PG8_STAGE(PG8_SB(1, 1), cB + hstep + kstep, voffB);
;         PG8_WAIT_V(6); PG8_BAR;
.Lgb_done_6:
	s_or_b64 exec, exec, s[84:85]
	s_barrier
	s_add_i32 s36, 0, 0x23088
	s_mov_b32 s33, s20
	s_mov_b32 s37, s26
	v_mov_b32_e32 v0, s36
	ds_read_b64 v[0:1], v0
	v_mov_b32_e32 v9, v230
	s_cmpk_lt_i32 s33, 0xb00
	v_readfirstlane_b32 s3, v9
	s_waitcnt lgkmcnt(0)
	v_readfirstlane_b32 s7, v1
	v_readfirstlane_b32 s6, v0
	s_cbranch_scc0 .LBB0_2878
	v_lshlrev_b32_e32 v0, 4, v9
	v_add_u32_e32 v1, 0x2000, v0
	v_ashrrev_i32_e32 v2, 31, v1
	v_lshrrev_b32_e32 v2, 22, v2
	v_add_u32_e32 v2, v1, v2
	v_ashrrev_i32_e32 v8, 10, v2
	v_mul_i32_i24_e32 v2, 0x400, v8
	v_sub_u32_e32 v1, v1, v2
	v_lshrrev_b32_e32 v2, 4, v1
	v_bitop3_b32 v1, v2, v1, 32 bitop3:0x6c
	v_ashrrev_i32_e32 v2, 31, v1
	v_lshrrev_b32_e32 v2, 26, v2
	v_add_u32_e32 v2, v1, v2
	v_lshlrev_b32_e32 v3, 3, v8
	v_ashrrev_i32_e32 v10, 6, v2
	v_and_b32_e32 v3, -16, v3
	v_add_u32_e32 v3, v10, v3
	v_and_b32_e32 v4, 3, v10
	s_mov_b32 s0, 0xfffe0
	v_lshrrev_b32_e32 v5, 2, v3
	v_lshlrev_b32_e32 v6, 1, v3
	v_and_b32_e32 v2, 0xc0, v2
	v_and_or_b32 v4, v3, s0, v4
	v_and_b32_e32 v5, 4, v5
	v_and_b32_e32 v6, 24, v6
	v_sub_u32_e32 v1, v1, v2
	v_mov_b32_e32 v2, 1
	v_or3_b32 v4, v4, v5, v6
	v_lshlrev_b32_e32 v5, 5, v8
	v_ashrrev_i16_sdwa v1, v2, sext(v1) dst_sel:DWORD dst_unused:UNUSED_PAD src0_sel:DWORD src1_sel:BYTE_0
	v_and_b32_e32 v5, 32, v5
	v_bfe_i32 v11, v1, 0, 16
	v_add_lshl_u32 v1, v5, v11, 1
	v_lshl_add_u32 v128, v4, 12, v1
	v_lshl_add_u32 v130, v3, 12, v1
	v_bfe_i32 v1, v9, 27, 1
	v_lshrrev_b32_e32 v1, 22, v1
	v_add_u32_e32 v1, v0, v1
	v_and_b32_e32 v1, 0xfffffc00, v1
	v_sub_u32_e32 v0, v0, v1
	v_lshrrev_b32_e32 v1, 4, v0
	v_ashrrev_i32_e32 v3, 31, v9
	v_bitop3_b32 v0, v1, v0, 32 bitop3:0x6c
	v_lshrrev_b32_e32 v3, 26, v3
	v_ashrrev_i32_e32 v1, 31, v0
	v_add_u32_e32 v3, v9, v3
	s_add_u32 s38, s6, 0x18600000
	v_lshrrev_b32_e32 v1, 26, v1
	v_ashrrev_i32_e32 v13, 6, v3
	s_addc_u32 s39, s7, 0
	v_add_u32_e32 v1, v0, v1
	v_lshlrev_b32_e32 v3, 3, v13
	s_add_u32 s40, s6, 0x10200000
	v_ashrrev_i32_e32 v12, 6, v1
	v_and_b32_e32 v3, -16, v3
	s_addc_u32 s41, s7, 0
	v_add_u32_e32 v3, v12, v3
	v_and_b32_e32 v4, 3, v12
	s_ashr_i32 s43, s33, 31
	v_and_or_b32 v4, v3, s0, v4
	s_lshr_b32 s0, s43, 29
	s_add_i32 s0, s33, s0
	s_ashr_i32 s8, s3, 6
	s_ashr_i32 s1, s0, 3
	s_and_b32 s0, s0, -8
	s_ashr_i32 s10, s3, 8
	s_lshl_b32 s42, s8, 10
	s_sub_i32 s0, s33, s0
	s_cmp_lt_i32 s0, 0
	s_movk_i32 s44, 0x161
	s_cselect_b32 s2, s44, 0x160
	s_mul_i32 s0, s0, s2
	s_add_i32 s0, s0, s1
	s_mul_hi_i32 s1, s0, 0x2e8ba2e9
	s_lshr_b32 s2, s1, 31
	s_ashr_i32 s1, s1, 6
	s_add_i32 s1, s1, s2
	s_lshl_b32 s4, s1, 3
	s_mulk_i32 s1, 0x160
	s_sub_i32 s0, s0, s1
	s_bfe_u32 s1, s0, 0x3001c
	s_add_i32 s1, s0, s1
	s_sext_i32_i16 s2, s1
	s_and_b32 s1, s1, 0xfff8
	s_sub_i32 s0, s0, s1
	s_sext_i32_i16 s0, s0
	v_lshrrev_b32_e32 v5, 2, v3
	v_lshlrev_b32_e32 v6, 1, v3
	v_and_b32_e32 v1, 0xc0, v1
	s_lshr_b32 s2, s2, 3
	s_add_i32 s24, s4, s0
	v_and_b32_e32 v5, 4, v5
	v_and_b32_e32 v6, 24, v6
	v_sub_u32_e32 v0, v0, v1
	s_ashr_i32 s25, s24, 31
	s_bfe_i64 s[4:5], s[2:3], 0x100000
	v_or3_b32 v4, v4, v5, v6
	v_lshlrev_b32_e32 v5, 5, v13
	v_ashrrev_i16_sdwa v0, v2, sext(v0) dst_sel:DWORD dst_unused:UNUSED_PAD src0_sel:DWORD src1_sel:BYTE_0
	s_lshl_b64 s[0:1], s[24:25], 20
	s_lshl_b64 s[4:5], s[4:5], 20
	v_and_b32_e32 v5, 32, v5
	v_bfe_i32 v14, v0, 0, 16
	s_add_u32 s30, s40, s4
	v_add_lshl_u32 v0, v5, v14, 1
	s_addc_u32 s31, s41, s5
	s_add_i32 s25, s42, 0
	v_lshl_add_u32 v132, v4, 12, v0
	s_add_i32 m0, s25, 0x10000
	v_lshl_add_u32 v134, v3, 12, v0
	global_load_lds_dwordx4 v132, s[30:31]
	s_add_i32 m0, s25, 0x12000
	s_add_u32 s4, s30, 0x80000
	global_load_lds_dwordx4 v128, s[30:31]
	s_addc_u32 s5, s31, 0
	s_add_i32 m0, s25, 0x14000
	v_mov_b32_e32 v133, 0
	global_load_lds_dwordx4 v132, s[4:5]
	s_add_i32 m0, s25, 0x16000
	s_add_u32 s28, s38, s0
	s_addc_u32 s29, s39, s1
	s_add_i32 s45, s25, 0x2000
	global_load_lds_dwordx4 v128, s[4:5]
	s_mov_b32 m0, s25
	s_add_u32 s0, s28, 0x80000
	global_load_lds_dwordx4 v134, s[28:29]
	s_mov_b32 m0, s45
	s_addc_u32 s1, s29, 0
	s_add_i32 s46, s25, 0x4000
	global_load_lds_dwordx4 v130, s[28:29]
	s_mov_b32 m0, s46
	s_add_i32 s47, s25, 0x6000
	global_load_lds_dwordx4 v134, s[0:1]
	s_mov_b32 m0, s47
	v_mov_b32_e32 v129, v133
	global_load_lds_dwordx4 v130, s[0:1]
	v_mov_b32_e32 v135, v133
	v_mov_b32_e32 v131, v133
	s_cmp_eq_u32 s10, 1
	v_lshl_add_u64 v[6:7], s[30:31], 0, v[132:133]
	v_lshl_add_u64 v[4:5], s[30:31], 0, v[128:129]
	v_lshl_add_u64 v[0:1], s[28:29], 0, v[134:135]
	s_cselect_b64 s[0:1], -1, 0
	s_cmp_lg_u32 s10, 1
	v_lshl_add_u64 v[2:3], s[28:29], 0, v[130:131]
	s_cbranch_scc1 .LBB0_2865
	s_barrier
